# grid barriers 1-3: no per-workgroup L1 invalidate after the release (every buffer the next phase reads is loaded for the first time in this launch); barriers 4-5 keep theirs (z at ws+0 is re-read afte
# speedup vs baseline: 1.0514x; 1.0073x over previous
; DI unsigned xb_ld(unsigned* p) { return __hip_atomic_load(p, __ATOMIC_RELAXED, __HIP_MEMORY_SCOPE_AGENT); }
; #define XB_SPIN(cond, bar) do { unsigned _sp = 0; while (cond) { __builtin_amdgcn_s_sleep(2); \
;     if ((++_sp & 255u) == 0u) { if (xb_ld(&(bar)[XB_TMO])) break; if (_sp > XB_SPIN_CAP) { atomicAdd(&(bar)[XB_TMO], 1u); break; } } } } while (0)
; DI void xcd_barrier(const XcdBarrier& b) {
;     ...
;             XB_SPIN(xb_ld(&bar[XB_XGEN(b.x)]) == gen, bar);
;             __builtin_amdgcn_fence(__ATOMIC_ACQUIRE, "agent");
;             asm volatile("s_waitcnt vmcnt(0)" ::: "memory");
.LBB0_73:
	s_or_b64 exec, exec, s[12:13]
	s_waitcnt vmcnt(0)
	s_waitcnt vmcnt(0)

; DI unsigned xb_add(unsigned* p, unsigned v) { return __hip_atomic_fetch_add(p, v, __ATOMIC_RELAXED, __HIP_MEMORY_SCOPE_AGENT); }
; DI void xcd_barrier(const XcdBarrier& b) {
;     ...
;             __builtin_amdgcn_fence(__ATOMIC_ACQUIRE, "agent");
;             xb_add(&bar[XB_XGEN(b.x)], 1u);
.LBB0_91:
	s_or_b64 exec, exec, s[10:11]
	s_mov_b64 s[6:7], exec
	v_mbcnt_lo_u32_b32 v2, s6, 0
	v_mbcnt_hi_u32_b32 v2, s7, v2
	v_cmp_eq_u32_e32 vcc, 0, v2
	s_waitcnt vmcnt(0)
	s_and_saveexec_b64 s[10:11], vcc
	s_cbranch_execz .LBB0_93
	s_bcnt1_i32_b64 s6, s[6:7]
	v_mov_b32_e32 v2, 0x2000
	v_mov_b32_e32 v3, s6
	global_atomic_add v2, v3, s[8:9] offset:1024

; DI unsigned xb_ld(unsigned* p) { return __hip_atomic_load(p, __ATOMIC_RELAXED, __HIP_MEMORY_SCOPE_AGENT); }
; #define XB_SPIN(cond, bar) do { unsigned _sp = 0; while (cond) { __builtin_amdgcn_s_sleep(2); \
;     if ((++_sp & 255u) == 0u) { if (xb_ld(&(bar)[XB_TMO])) break; if (_sp > XB_SPIN_CAP) { atomicAdd(&(bar)[XB_TMO], 1u); break; } } } } while (0)
; DI void xcd_barrier(const XcdBarrier& b) {
;     ...
;             XB_SPIN(xb_ld(&bar[XB_XGEN(b.x)]) == gen, bar);
;             __builtin_amdgcn_fence(__ATOMIC_ACQUIRE, "agent");
;             asm volatile("s_waitcnt vmcnt(0)" ::: "memory");
.LBB0_175:
	s_or_b64 exec, exec, s[8:9]
	s_waitcnt vmcnt(0)
	s_waitcnt vmcnt(0)

; DI unsigned xb_add(unsigned* p, unsigned v) { return __hip_atomic_fetch_add(p, v, __ATOMIC_RELAXED, __HIP_MEMORY_SCOPE_AGENT); }
; DI void xcd_barrier(const XcdBarrier& b) {
;     ...
;             __builtin_amdgcn_fence(__ATOMIC_ACQUIRE, "agent");
;             xb_add(&bar[XB_XGEN(b.x)], 1u);
.LBB0_193:
	s_or_b64 exec, exec, s[6:7]
	s_mov_b64 s[2:3], exec
	v_mbcnt_lo_u32_b32 v2, s2, 0
	v_mbcnt_hi_u32_b32 v2, s3, v2
	v_cmp_eq_u32_e32 vcc, 0, v2
	s_waitcnt vmcnt(0)
	s_and_saveexec_b64 s[6:7], vcc
	s_cbranch_execz .LBB0_195
	s_bcnt1_i32_b64 s2, s[2:3]
	v_mov_b32_e32 v2, 0x2000
	v_mov_b32_e32 v3, s2
	global_atomic_add v2, v3, s[4:5] offset:1024
